# S5 step top: out-projection waves wait vmcnt(4) (u load older than their four result stores; load and stores as global ops)
# speedup vs baseline: 1.0027x; 1.0027x over previous
; __device__ __forceinline__ void s5_unit(const Args& A, char* lds, int b, int g) {
;     ...
;     for (int i = 0; i < SEQL / 64 + 2; ++i) {
;         if (i < SEQL / 64) { float* BU = (float*)(lds + S5_BU) + (i & 1) * (64 * 132); f32x16 acc = {};
;             acc = __builtin_amdgcn_mfma_f32_32x32x16_bf16(un, bfrag, acc, 0, 0, 0);
;             if (ntile == 0) *(bf16x8*)((bf16*)(lds + S5_US) + ((i & 3) * 64 + ttile * 32 + r32) * 16 + 8 * hi) = un;
;             if (i + 1 < SEQL / 64) un = *(const bf16x8*)(pU + (size_t)(i + 1) * 64 * LD1);
.LBB0_1348:
	s_add_i32 s45, s8, 2
	s_cmp_gt_u32 s45, 31
	s_cbranch_scc1 .LBB0_1353
	s_cmp_gt_u32 s99, 3
	s_cbranch_scc0 .Ls5_wfull
	s_cmp_gt_u32 s45, 2
	s_cbranch_scc0 .Ls5_wfull
	s_waitcnt vmcnt(4) lgkmcnt(0)
	s_branch .Ls5_wjoin

; __device__ __forceinline__ void s5_unit(const Args& A, char* lds, int b, int g) {
;     ...
;             if (i + 1 < SEQL / 64) un = *(const bf16x8*)(pU + (size_t)(i + 1) * 64 * LD1);
.LBB0_1351:
	global_load_dwordx4 v[36:39], v[52:53], off

; __device__ __forceinline__ unsigned f2bf(float f) { return pk2(f, f) & 0xffffu; }
; __device__ __forceinline__ float bf2f(unsigned short h) { return __uint_as_float(((unsigned)h) << 16); }
; __device__ __forceinline__ float gelu_tanh(float x) { const float u = 0.7978845608028654f * (x + 0.044715f * x * x * x); const float e = __expf(2.f * u); const float t = 1.f - 2.f * __builtin_amdgcn_rcpf(e + 1.f); return 0.5f * x * (1.f + t); }
; __device__ __forceinline__ void s5_unit(const Args& A, char* lds, int b, int g) {
;     ...
;         if (wave >= 4 && i >= 2) { const bf16* SS = (const bf16*)(lds + S5_SS) + ((i - 2) & 1) * (64 * 136); const int mt = wave - 4; const size_t m0 = rb0 + (size_t)(i - 2) * 64;
;             unsigned short uv[4];
; #pragma unroll
;             for (int r = 0; r < 4; ++r) uv[r] = ((const bf16*)(lds + S5_US))[(((i - 2) & 3) * 64 + mt * 16 + 4 * fq + r) * 16 + fr];
;             f32x4m acc = (f32x4m){0.f, 0.f, 0.f, 0.f};
; #pragma unroll
;             for (int ks = 0; ks < 4; ++ks) { const bf16x8 af = *(const bf16x8*)(SS + (mt * 16 + fr) * 136 + ks * 32 + 8 * fq); acc = __builtin_amdgcn_mfma_f32_16x16x32_bf16(af, cfrag[ks], acc, 0, 0, 0); }
; #pragma unroll
;             for (int r = 0; r < 4; ++r) { const size_t m = m0 + mt * 16 + 4 * fq + r; YD[m * 2048 + 1024 + g * 16 + fr] = (bf16)f2bf(gelu_tanh(acc[r] + dskip * bf2f(uv[r]))); } }
.LBB0_1360:
	s_cmp_gt_u32 s45, 1
	s_cselect_b64 s[22:23], -1, 0
	s_and_b64 s[22:23], s[18:19], s[22:23]
	s_andn2_b64 vcc, exec, s[22:23]
	s_cbranch_vccnz .LBB0_1347
	s_and_b32 s22, 1, s45
	s_and_b32 s23, s44, 0xc0
	s_cmp_eq_u32 s22, 1
	s_cselect_b32 s22, 0x4400, 0
	v_add_u32_e32 v12, s22, v64
	ds_read_b128 v[0:3], v12
	ds_read_b128 v[4:7], v12 offset:64
	v_add_u32_e32 v8, s23, v62
	v_lshl_add_u32 v40, v8, 5, v63
	ds_read_b128 v[8:11], v12 offset:128
	s_waitcnt lgkmcnt(0)
	v_mfma_f32_16x16x32_bf16 v[0:3], v[0:3], v[16:19], 0
	ds_read_b128 v[12:15], v12 offset:192
	s_lshl_b64 s[22:23], s[8:9], 18
	v_lshl_add_u64 v[66:67], s[22:23], 0, v[50:51]
	v_mfma_f32_16x16x32_bf16 v[0:3], v[4:7], v[24:27], v[0:3]
	ds_read_u16 v6, v40
	ds_read_u16 v7, v40 offset:32
	ds_read_u16 v68, v40 offset:64
	ds_read_u16 v40, v40 offset:96
	v_lshl_add_u64 v[4:5], v[48:49], 0, v[66:67]
	s_waitcnt lgkmcnt(0)
	v_lshlrev_b32_e32 v6, 16, v6
	v_mfma_f32_16x16x32_bf16 v[0:3], v[8:11], v[28:31], v[0:3]
	v_lshlrev_b32_e32 v7, 16, v7
	v_mfma_f32_16x16x32_bf16 v[0:3], v[12:15], v[32:35], v[0:3]
	s_nop 7
	v_fma_f32 v0, v57, v6, v0
	v_mul_f32_e32 v6, 0x3d372713, v0
	v_mul_f32_e32 v6, v0, v6
	v_fma_f32 v6, v0, v6, v0
	v_mul_f32_e32 v6, 0x3f4c422a, v6
	v_add_f32_e32 v6, v6, v6
	v_mul_f32_e32 v6, 0x3fb8aa3b, v6
	v_exp_f32_e32 v6, v6
	v_fma_f32 v1, v57, v7, v1
	v_mul_f32_e32 v7, 0x3d372713, v1
	v_mul_f32_e32 v7, v1, v7
	v_add_f32_e32 v6, 1.0, v6
	v_rcp_f32_e32 v6, v6
	v_fma_f32 v7, v1, v7, v1
	v_mul_f32_e32 v0, 0.5, v0
	v_mul_f32_e32 v7, 0x3f4c422a, v7
	v_fma_f32 v6, v6, -2.0, 1.0
	v_add_f32_e32 v6, 1.0, v6
	v_mul_f32_e32 v0, v0, v6
	v_add_f32_e32 v7, v7, v7
	v_cvt_pk_bf16_f32 v0, v0, s0
	v_mul_f32_e32 v7, 0x3fb8aa3b, v7
	global_store_short v[4:5], v0, off offset:2048
	v_lshlrev_b32_e32 v4, 16, v68
	v_exp_f32_e32 v7, v7
	v_fma_f32 v2, v57, v4, v2
	v_mul_f32_e32 v4, 0x3d372713, v2
	v_mul_f32_e32 v4, v2, v4
	v_fma_f32 v4, v2, v4, v2
	v_add_f32_e32 v7, 1.0, v7
	v_mul_f32_e32 v4, 0x3f4c422a, v4
	v_rcp_f32_e32 v7, v7
	v_add_f32_e32 v4, v4, v4
	v_mul_f32_e32 v4, 0x3fb8aa3b, v4
	v_exp_f32_e32 v4, v4
	v_fma_f32 v0, v7, -2.0, 1.0
	v_mul_f32_e32 v1, 0.5, v1
	v_add_f32_e32 v0, 1.0, v0
	v_mul_f32_e32 v0, v1, v0
	v_add_f32_e32 v1, 1.0, v4
	v_cvt_pk_bf16_f32 v5, v0, s0
	v_or_b32_e32 v0, 0x1000, v66
	v_rcp_f32_e32 v4, v1
	v_mov_b32_e32 v1, v67
	v_lshl_add_u64 v[0:1], v[48:49], 0, v[0:1]
	global_store_short v[0:1], v5, off offset:2048
	v_mul_f32_e32 v1, 0.5, v2
	v_lshlrev_b32_e32 v2, 16, v40
	v_fmac_f32_e32 v3, v57, v2
	v_mul_f32_e32 v2, 0x3d372713, v3
	v_mul_f32_e32 v2, v3, v2
	v_fma_f32 v2, v3, v2, v3
	v_mul_f32_e32 v2, 0x3f4c422a, v2
	v_add_f32_e32 v2, v2, v2
	v_mul_f32_e32 v2, 0x3fb8aa3b, v2
	v_exp_f32_e32 v2, v2
	v_fma_f32 v0, v4, -2.0, 1.0
	v_add_f32_e32 v0, 1.0, v0
	v_mul_f32_e32 v0, v1, v0
	v_add_f32_e32 v1, 1.0, v2
	v_rcp_f32_e32 v2, v1
	v_cvt_pk_bf16_f32 v4, v0, s0
	v_or_b32_e32 v0, 0x2000, v66
	v_mov_b32_e32 v1, v67
	v_lshl_add_u64 v[0:1], v[48:49], 0, v[0:1]
	global_store_short v[0:1], v4, off offset:2048
	v_fma_f32 v0, v2, -2.0, 1.0
	v_mul_f32_e32 v1, 0.5, v3
	v_add_f32_e32 v0, 1.0, v0
	v_mul_f32_e32 v0, v1, v0
	v_or_b32_e32 v66, 0x3000, v66
	v_cvt_pk_bf16_f32 v2, v0, s0
	v_lshl_add_u64 v[0:1], v[48:49], 0, v[66:67]
	global_store_short v[0:1], v2, off offset:2048
	s_branch .LBB0_1347
